# pair the two importance LDS read-modify-writes per tau block into one round trip (on top of pitch-160)
# baseline (speedup 1.0000x reference)
; template <int CTRL> __device__ __forceinline__ float dppf(float x) { return __builtin_bit_cast(float, __builtin_amdgcn_mov_dpp(__builtin_bit_cast(int, x), CTRL, 0xf, 0xf, true)); }
; template <int MODE>
; __device__ __forceinline__ void nsa_soft(f32x4 (&st)[4], const float (&Bl)[16], float cl, bool fast, int keybase, int t, bool sel, float& m2, float& l, f32x4 (&o)[4], float lfin, LAS float* imp, int lane) {
;     ...
;     if (MODE == 1) {
;         const float sh = cl - lfin;
; #pragma unroll
;         for (int tau = 0; tau < 4; ++tau) {
; #pragma unroll
;             for (int r = 0; r < 4; ++r) st[tau][r] = __builtin_amdgcn_exp2f(st[tau][r] + sh);
;             float ps = (st[tau][0] + st[tau][1]) + (st[tau][2] + st[tau][3]), p3 = st[tau][3];
;             ps += dppf<DPP_XOR1>(ps); ps += dppf<DPP_XOR2>(ps); p3 += dppf<DPP_XOR1>(p3); p3 += dppf<DPP_XOR2>(p3);
;             const int j0 = (keybase >> 2) + 8 * (tau >> 1) + 2 * kg + (tau & 1);
;             if ((lane & 3) == 0) { const int tk = (lane & 15) >> 2; imp[tk * 256 + j0] += ps; if (j0 + 1 < 256) imp[tk * 256 + j0 + 1] += p3; }
;         }
.LBB0_925:
	v_add_u32_e32 v252, s48, v161
	v_add_u32_e32 v227, 0xfffffc10, v252
	v_cvt_f32_i32_e32 v227, v227
	s_lshr_b32 s10, s20, 2
	v_or_b32_e32 v253, s10, v208
	v_cmp_gt_u32_e64 s[10:11], s23, v253
	v_fma_f32 v251, v154, v227, -v163
	v_add_f32_e32 v191, v251, v191
	v_add_f32_e32 v190, v251, v190
	v_exp_f32_e32 v227, v191
	v_add_f32_e32 v191, v251, v192
	v_add_f32_e32 v192, v251, v193
	v_exp_f32_e32 v190, v190
	v_exp_f32_e32 v191, v191
	v_exp_f32_e32 v192, v192
	v_add_f32_e32 v193, v190, v227
	v_add_f32_e32 v228, v191, v192
	v_add_f32_e32 v193, v193, v228
	s_nop 0
	v_add_f32_dpp v228, v192, v192 quad_perm:[1,0,3,2] row_mask:0xf bank_mask:0xf bound_ctrl:1
	v_add_f32_dpp v230, v193, v193 quad_perm:[1,0,3,2] row_mask:0xf bank_mask:0xf bound_ctrl:1
	s_nop 0
	v_mov_b32_dpp v229, v228 quad_perm:[2,3,0,1] row_mask:0xf bank_mask:0xf bound_ctrl:1
	v_lshl_add_u32 v193, v253, 2, v194
	v_mov_b32_dpp v231, v230 quad_perm:[2,3,0,1] row_mask:0xf bank_mask:0xf bound_ctrl:1
	s_and_saveexec_b64 s[12:13], s[6:7]
	s_cbranch_execz .LBB0_928
	v_add_f32_e32 v230, v230, v231
	v_add_f32_e32 v228, v228, v229
	ds_read_b32 v231, v193
	ds_read_b32 v229, v193 offset:4
	s_waitcnt lgkmcnt(0)
	v_add_f32_e32 v230, v230, v231
	ds_write_b32 v193, v230
	s_and_b64 exec, exec, s[10:11]
	s_cbranch_execz .LBB0_928
	v_add_f32_e32 v228, v228, v229
	ds_write_b32 v193, v228 offset:4
.LBB0_928:
	s_or_b64 exec, exec, s[12:13]
	v_add_f32_e32 v188, v251, v188
	v_add_f32_e32 v189, v251, v189
	v_add_f32_e32 v186, v251, v186
	v_add_f32_e32 v187, v251, v187
	v_exp_f32_e32 v188, v188
	v_exp_f32_e32 v189, v189
	v_exp_f32_e32 v186, v186
	v_exp_f32_e32 v187, v187
	s_movk_i32 s12, 0xfe
	v_add_f32_e32 v228, v188, v189
	v_cmp_gt_u32_e64 s[12:13], s12, v253
	v_add_f32_e32 v229, v186, v187
	v_add_f32_e32 v228, v228, v229
	s_nop 1
	v_add_f32_dpp v230, v228, v228 quad_perm:[1,0,3,2] row_mask:0xf bank_mask:0xf bound_ctrl:1
	v_add_f32_dpp v228, v187, v187 quad_perm:[1,0,3,2] row_mask:0xf bank_mask:0xf bound_ctrl:1
	s_nop 0
	v_mov_b32_dpp v231, v230 quad_perm:[2,3,0,1] row_mask:0xf bank_mask:0xf bound_ctrl:1
	v_mov_b32_dpp v229, v228 quad_perm:[2,3,0,1] row_mask:0xf bank_mask:0xf bound_ctrl:1
	s_and_saveexec_b64 s[14:15], s[6:7]
	s_cbranch_execz .LBB0_931
	v_add_f32_e32 v230, v230, v231
	v_add_f32_e32 v228, v228, v229
	ds_read_b32 v231, v193 offset:4
	ds_read_b32 v229, v193 offset:8
	s_waitcnt lgkmcnt(0)
	v_add_f32_e32 v230, v230, v231
	ds_write_b32 v193, v230 offset:4
	s_and_b64 exec, exec, s[12:13]
	s_cbranch_execz .LBB0_931
	v_add_f32_e32 v228, v228, v229
	ds_write_b32 v193, v228 offset:8
.LBB0_931:
	s_or_b64 exec, exec, s[14:15]
	v_add_f32_e32 v184, v251, v184
	v_add_f32_e32 v182, v251, v182
	v_exp_f32_e32 v228, v184
	v_add_f32_e32 v184, v251, v185
	v_exp_f32_e32 v229, v182
	v_add_f32_e32 v182, v251, v183
	v_exp_f32_e32 v230, v184
	v_exp_f32_e32 v231, v182
	s_movk_i32 s14, 0xf7
	v_cmp_gt_u32_e64 s[14:15], s14, v253
	v_add_f32_e32 v182, v228, v230
	v_add_f32_e32 v183, v229, v231
	v_add_f32_e32 v182, v182, v183
	s_nop 1
	v_add_f32_dpp v184, v182, v182 quad_perm:[1,0,3,2] row_mask:0xf bank_mask:0xf bound_ctrl:1
	v_add_f32_dpp v182, v231, v231 quad_perm:[1,0,3,2] row_mask:0xf bank_mask:0xf bound_ctrl:1
	s_nop 0
	v_mov_b32_dpp v185, v184 quad_perm:[2,3,0,1] row_mask:0xf bank_mask:0xf bound_ctrl:1
	v_mov_b32_dpp v183, v182 quad_perm:[2,3,0,1] row_mask:0xf bank_mask:0xf bound_ctrl:1
	s_and_saveexec_b64 s[16:17], s[6:7]
	s_cbranch_execz .LBB0_934
	v_add_f32_e32 v184, v184, v185
	v_add_f32_e32 v182, v182, v183
	ds_read_b32 v185, v193 offset:32
	ds_read_b32 v183, v193 offset:36
	s_waitcnt lgkmcnt(0)
	v_add_f32_e32 v184, v184, v185
	ds_write_b32 v193, v184 offset:32
	s_and_b64 exec, exec, s[14:15]
	s_cbranch_execz .LBB0_934
	v_add_f32_e32 v182, v182, v183
	ds_write_b32 v193, v182 offset:36
.LBB0_934:
	s_or_b64 exec, exec, s[16:17]
	v_add_f32_e32 v180, v251, v180
	v_add_f32_e32 v178, v251, v178
	v_exp_f32_e32 v248, v180
	v_add_f32_e32 v180, v251, v181
	v_exp_f32_e32 v249, v178
	v_add_f32_e32 v178, v251, v179
	v_exp_f32_e32 v250, v180
	v_exp_f32_e32 v251, v178
	s_movk_i32 s16, 0xf6
	v_cmp_gt_u32_e64 s[16:17], s16, v253
	v_add_f32_e32 v178, v248, v250
	v_add_f32_e32 v179, v249, v251
	v_add_f32_e32 v178, v178, v179
	s_nop 1
	v_add_f32_dpp v180, v178, v178 quad_perm:[1,0,3,2] row_mask:0xf bank_mask:0xf bound_ctrl:1
	v_add_f32_dpp v178, v251, v251 quad_perm:[1,0,3,2] row_mask:0xf bank_mask:0xf bound_ctrl:1
	s_nop 0
	v_mov_b32_dpp v181, v180 quad_perm:[2,3,0,1] row_mask:0xf bank_mask:0xf bound_ctrl:1
	v_mov_b32_dpp v179, v178 quad_perm:[2,3,0,1] row_mask:0xf bank_mask:0xf bound_ctrl:1
	s_and_saveexec_b64 s[44:45], s[6:7]
	s_cbranch_execz .LBB0_937
	v_add_f32_e32 v180, v180, v181
	v_add_f32_e32 v178, v178, v179
	ds_read_b32 v181, v193 offset:36
	ds_read_b32 v179, v193 offset:40
	s_waitcnt lgkmcnt(0)
	v_add_f32_e32 v180, v180, v181
	ds_write_b32 v193, v180 offset:36
	s_and_b64 exec, exec, s[16:17]
	s_cbranch_execz .LBB0_937
	v_add_f32_e32 v178, v178, v179
	ds_write_b32 v193, v178 offset:40

; template <int CTRL> __device__ __forceinline__ float dppf(float x) { return __builtin_bit_cast(float, __builtin_amdgcn_mov_dpp(__builtin_bit_cast(int, x), CTRL, 0xf, 0xf, true)); }
; template <int MODE>
; __device__ __forceinline__ void nsa_soft(f32x4 (&st)[4], const float (&Bl)[16], float cl, bool fast, int keybase, int t, bool sel, float& m2, float& l, f32x4 (&o)[4], float lfin, LAS float* imp, int lane) {
;     ...
;     if (MODE == 1) {
;         const float sh = cl - lfin;
; #pragma unroll
;         for (int tau = 0; tau < 4; ++tau) {
; #pragma unroll
;             for (int r = 0; r < 4; ++r) st[tau][r] = __builtin_amdgcn_exp2f(st[tau][r] + sh);
;             float ps = (st[tau][0] + st[tau][1]) + (st[tau][2] + st[tau][3]), p3 = st[tau][3];
;             ps += dppf<DPP_XOR1>(ps); ps += dppf<DPP_XOR2>(ps); p3 += dppf<DPP_XOR1>(p3); p3 += dppf<DPP_XOR2>(p3);
;             const int j0 = (keybase >> 2) + 8 * (tau >> 1) + 2 * kg + (tau & 1);
;             if ((lane & 3) == 0) { const int tk = (lane & 15) >> 2; imp[tk * 256 + j0] += ps; if (j0 + 1 < 256) imp[tk * 256 + j0 + 1] += p3; }
;         }
.LBB0_939:
	v_add_u32_e32 v72, 0xfffffc0c, v252
	v_cvt_f32_i32_e32 v72, v72
	v_fma_f32 v232, v154, v72, -v165
	v_add_f32_e32 v72, v232, v184
	v_add_f32_e32 v75, v232, v182
	v_add_f32_e32 v74, v232, v185
	v_exp_f32_e32 v73, v72
	v_exp_f32_e32 v72, v75
	v_add_f32_e32 v75, v232, v183
	v_exp_f32_e32 v74, v74
	v_exp_f32_e32 v75, v75
	v_add_f32_e32 v76, v73, v74
	v_add_f32_e32 v77, v72, v75
	v_add_f32_e32 v76, v76, v77
	s_nop 1
	v_add_f32_dpp v78, v76, v76 quad_perm:[1,0,3,2] row_mask:0xf bank_mask:0xf bound_ctrl:1
	v_add_f32_dpp v76, v75, v75 quad_perm:[1,0,3,2] row_mask:0xf bank_mask:0xf bound_ctrl:1
	s_nop 0
	v_mov_b32_dpp v79, v78 quad_perm:[2,3,0,1] row_mask:0xf bank_mask:0xf bound_ctrl:1
	v_mov_b32_dpp v77, v76 quad_perm:[2,3,0,1] row_mask:0xf bank_mask:0xf bound_ctrl:1
	s_and_saveexec_b64 s[40:41], s[6:7]
	s_cbranch_execz .LBB0_942
	v_add_f32_e32 v78, v78, v79
	v_add_f32_e32 v76, v76, v77
	ds_read_b32 v79, v193 offset:4096
	ds_read_b32 v77, v193 offset:4100
	s_waitcnt lgkmcnt(0)
	v_add_f32_e32 v78, v78, v79
	ds_write_b32 v193, v78 offset:4096
	s_and_b64 exec, exec, s[10:11]
	s_cbranch_execz .LBB0_942
	v_add_f32_e32 v76, v76, v77
	ds_write_b32 v193, v76 offset:4100
.LBB0_942:
	s_or_b64 exec, exec, s[40:41]
	v_add_f32_e32 v77, v232, v181
	v_add_f32_e32 v76, v232, v180
	v_exp_f32_e32 v78, v77
	v_add_f32_e32 v77, v232, v178
	v_add_f32_e32 v79, v232, v179
	v_exp_f32_e32 v76, v76
	v_exp_f32_e32 v77, v77
	v_exp_f32_e32 v79, v79
	v_add_f32_e32 v178, v76, v78
	v_add_f32_e32 v179, v77, v79
	v_add_f32_e32 v178, v178, v179
	s_nop 1
	v_add_f32_dpp v180, v178, v178 quad_perm:[1,0,3,2] row_mask:0xf bank_mask:0xf bound_ctrl:1
	v_add_f32_dpp v178, v79, v79 quad_perm:[1,0,3,2] row_mask:0xf bank_mask:0xf bound_ctrl:1
	s_nop 0
	v_mov_b32_dpp v181, v180 quad_perm:[2,3,0,1] row_mask:0xf bank_mask:0xf bound_ctrl:1
	v_mov_b32_dpp v179, v178 quad_perm:[2,3,0,1] row_mask:0xf bank_mask:0xf bound_ctrl:1
	s_and_saveexec_b64 s[10:11], s[6:7]
	s_cbranch_execz .LBB0_945
	v_add_f32_e32 v180, v180, v181
	v_add_f32_e32 v178, v178, v179
	ds_read_b32 v181, v193 offset:4100
	ds_read_b32 v179, v193 offset:4104
	s_waitcnt lgkmcnt(0)
	v_add_f32_e32 v180, v180, v181
	ds_write_b32 v193, v180 offset:4100
	s_and_b64 exec, exec, s[12:13]
	s_cbranch_execz .LBB0_945
	v_add_f32_e32 v178, v178, v179
	ds_write_b32 v193, v178 offset:4104
.LBB0_945:
	s_or_b64 exec, exec, s[10:11]
	v_add_f32_e32 v70, v232, v70
	v_add_f32_e32 v71, v232, v71
	v_add_f32_e32 v68, v232, v68
	v_add_f32_e32 v69, v232, v69
	v_exp_f32_e32 v70, v70
	v_exp_f32_e32 v71, v71
	v_exp_f32_e32 v68, v68
	v_exp_f32_e32 v69, v69
	v_add_f32_e32 v178, v70, v71
	v_add_f32_e32 v179, v68, v69
	v_add_f32_e32 v178, v178, v179
	s_nop 1
	v_add_f32_dpp v180, v178, v178 quad_perm:[1,0,3,2] row_mask:0xf bank_mask:0xf bound_ctrl:1
	v_add_f32_dpp v178, v69, v69 quad_perm:[1,0,3,2] row_mask:0xf bank_mask:0xf bound_ctrl:1
	s_nop 0
	v_mov_b32_dpp v181, v180 quad_perm:[2,3,0,1] row_mask:0xf bank_mask:0xf bound_ctrl:1
	v_mov_b32_dpp v179, v178 quad_perm:[2,3,0,1] row_mask:0xf bank_mask:0xf bound_ctrl:1
	s_and_saveexec_b64 s[10:11], s[6:7]
	s_cbranch_execz .LBB0_948
	v_add_f32_e32 v180, v180, v181
	v_add_f32_e32 v178, v178, v179
	ds_read_b32 v181, v193 offset:4128
	ds_read_b32 v179, v193 offset:4132
	s_waitcnt lgkmcnt(0)
	v_add_f32_e32 v180, v180, v181
	ds_write_b32 v193, v180 offset:4128
	s_and_b64 exec, exec, s[14:15]
	s_cbranch_execz .LBB0_948
	v_add_f32_e32 v178, v178, v179
	ds_write_b32 v193, v178 offset:4132
.LBB0_948:
	s_or_b64 exec, exec, s[10:11]
	v_add_f32_e32 v65, v232, v65
	v_add_f32_e32 v64, v232, v64
	v_exp_f32_e32 v178, v65
	v_add_f32_e32 v65, v232, v66
	v_add_f32_e32 v66, v232, v67
	v_exp_f32_e32 v64, v64
	v_exp_f32_e32 v65, v65
	v_exp_f32_e32 v66, v66
	v_add_f32_e32 v67, v64, v178
	v_add_f32_e32 v179, v65, v66
	v_add_f32_e32 v67, v67, v179
	s_nop 1
	v_add_f32_dpp v180, v67, v67 quad_perm:[1,0,3,2] row_mask:0xf bank_mask:0xf bound_ctrl:1
	v_add_f32_dpp v67, v66, v66 quad_perm:[1,0,3,2] row_mask:0xf bank_mask:0xf bound_ctrl:1
	s_nop 0
	v_mov_b32_dpp v181, v180 quad_perm:[2,3,0,1] row_mask:0xf bank_mask:0xf bound_ctrl:1
	v_mov_b32_dpp v179, v67 quad_perm:[2,3,0,1] row_mask:0xf bank_mask:0xf bound_ctrl:1
	s_and_saveexec_b64 s[10:11], s[6:7]
	s_cbranch_execz .LBB0_951
	v_add_f32_e32 v180, v180, v181
	v_add_f32_e32 v67, v67, v179
	ds_read_b32 v181, v193 offset:4132
	ds_read_b32 v179, v193 offset:4136
	s_waitcnt lgkmcnt(0)
	v_add_f32_e32 v180, v180, v181
	ds_write_b32 v193, v180 offset:4132
	s_and_b64 exec, exec, s[16:17]
	s_cbranch_execz .LBB0_951
	v_add_f32_e32 v67, v67, v179
	ds_write_b32 v193, v67 offset:4136
